# odd in-projection, transposed Fourier-input tiles: in-register 4x4 transpose + lane permutation so each store instruction writes full 128-byte lines (32 eight-byte stores per lane instead of 128 two-b
# baseline (speedup 1.0000x reference)
.Lrl_e0_1241:
	s_cmp_lt_i32 s42, 9
	s_cbranch_scc1 .Lxt_skip
	v_lshrrev_b32_e32 v0, 6, v191
	s_sub_i32 s0, s42, 9
	s_cmp_lt_i32 s44, 16
	s_cbranch_scc0 .Lxt_lat
	s_lshl_b32 s34, s44, 18
	s_lshl_b32 s0, s0, 9
	s_add_u32 s34, s34, s0
	s_add_u32 s34, s70, s34
	s_addc_u32 s35, s71, 0
	s_movk_i32 s29, 0x400
	s_branch .Lxt_go
.Lxt_lat:
	s_add_i32 s1, s44, -16
	s_lshr_b32 s7, s1, 3
	s_lshl_b32 s7, s7, 21
	s_and_b32 s1, s1, 7
	s_lshl_b32 s1, s1, 9
	s_lshl_b32 s0, s0, 12
	s_add_u32 s1, s1, s0
	s_add_u32 s34, s7, s1
	s_add_u32 s34, s72, s34
	s_addc_u32 s35, s73, 0
	s_movk_i32 s29, 0x2000
.Lxt_go:
	v_readfirstlane_b32 s15, v0
	s_and_b32 s18, s15, 3
	s_lshr_b32 s15, s15, 2
	s_lshl_b32 s18, s18, 5
	s_mul_i32 s18, s18, s29
	s_lshl_b32 s15, s15, 7
	s_add_u32 s18, s18, s15
	s_add_u32 s34, s34, s18
	s_addc_u32 s35, s35, 0
	v_and_b32_e32 v0, 63, v191
	v_lshrrev_b32_e32 v150, 4, v0
	v_lshlrev_b32_e32 v150, 3, v150
	v_mul_u32_u24_e32 v150, s29, v150
	v_and_b32_e32 v151, 15, v0
	v_lshl_add_u32 v150, v151, 3, v150
	v_and_b32_e32 v176, 3, v0
	v_bfe_u32 v177, v0, 2, 2
	v_lshl_or_b32 v176, v176, 2, v177
	v_and_b32_e32 v177, 48, v0
	v_or_b32_e32 v176, v176, v177
	v_lshlrev_b32_e32 v176, 2, v176
	v_mov_b32_e32 v151, 0
	s_lshl_b32 s0, s29, 2
	s_mov_b32 s1, 0
	s_lshl_b32 s20, s29, 7
	s_mov_b32 s21, 0
	v_lshl_add_u64 v[152:153], s[34:35], 0, v[150:151]
	v_lshl_add_u64 v[162:163], v[152:153], 0, s[0:1]
	v_lshl_add_u64 v[164:165], v[152:153], 0, s[20:21]
	v_lshl_add_u64 v[166:167], v[164:165], 0, s[0:1]
	s_mov_b32 s0, s29
	s_lshl_b32 s20, s29, 1
	s_add_u32 s60, s20, s29
	s_mov_b32 s61, 0
	s_mov_b32 s48, 0x55555555
	s_mov_b32 s49, 0x55555555
	s_mov_b32 s50, 0xaaaaaaaa
	s_mov_b32 s51, 0xaaaaaaaa
	s_mov_b32 s52, 0x33333333
	s_mov_b32 s53, 0x33333333
	s_mov_b32 s54, 0xcccccccc
	s_mov_b32 s55, 0xcccccccc
	s_mov_b64 vcc, s[48:49]
	s_nop 0
	v_cndmask_b32_dpp v140, v110, v126, vcc quad_perm:[1,0,3,2] row_mask:0xf bank_mask:0xf
	v_cndmask_b32_dpp v141, v78, v94, vcc quad_perm:[1,0,3,2] row_mask:0xf bank_mask:0xf
	v_cndmask_b32_dpp v142, v46, v62, vcc quad_perm:[1,0,3,2] row_mask:0xf bank_mask:0xf
	v_cndmask_b32_dpp v143, v14, v30, vcc quad_perm:[1,0,3,2] row_mask:0xf bank_mask:0xf
	s_mov_b64 vcc, s[50:51]
	s_nop 0
	v_cndmask_b32_dpp v110, v126, v110, vcc quad_perm:[1,0,3,2] row_mask:0xf bank_mask:0xf
	v_cndmask_b32_dpp v78, v94, v78, vcc quad_perm:[1,0,3,2] row_mask:0xf bank_mask:0xf
	v_cndmask_b32_dpp v46, v62, v46, vcc quad_perm:[1,0,3,2] row_mask:0xf bank_mask:0xf
	v_cndmask_b32_dpp v14, v30, v14, vcc quad_perm:[1,0,3,2] row_mask:0xf bank_mask:0xf
	s_mov_b64 vcc, s[52:53]
	s_nop 0
	v_cndmask_b32_dpp v126, v141, v140, vcc quad_perm:[2,3,0,1] row_mask:0xf bank_mask:0xf
	v_cndmask_b32_dpp v94, v78, v110, vcc quad_perm:[2,3,0,1] row_mask:0xf bank_mask:0xf
	v_cndmask_b32_dpp v62, v143, v142, vcc quad_perm:[2,3,0,1] row_mask:0xf bank_mask:0xf
	v_cndmask_b32_dpp v30, v14, v46, vcc quad_perm:[2,3,0,1] row_mask:0xf bank_mask:0xf
	s_mov_b64 vcc, s[54:55]
	s_nop 0
	v_cndmask_b32_dpp v141, v140, v141, vcc quad_perm:[2,3,0,1] row_mask:0xf bank_mask:0xf
	v_cndmask_b32_dpp v78, v110, v78, vcc quad_perm:[2,3,0,1] row_mask:0xf bank_mask:0xf
	v_cndmask_b32_dpp v143, v142, v143, vcc quad_perm:[2,3,0,1] row_mask:0xf bank_mask:0xf
	v_cndmask_b32_dpp v14, v46, v14, vcc quad_perm:[2,3,0,1] row_mask:0xf bank_mask:0xf
	v_cvt_pk_bf16_f32 v126, v126, v94
	v_cvt_pk_bf16_f32 v110, v141, v78
	v_cvt_pk_bf16_f32 v62, v62, v30
	v_cvt_pk_bf16_f32 v46, v143, v14
	ds_bpermute_b32 v172, v176, v126
	ds_bpermute_b32 v173, v176, v110
	ds_bpermute_b32 v174, v176, v62
	ds_bpermute_b32 v175, v176, v46
	v_lshl_add_u64 v[188:189], v[152:153], 0, s[0:1]
	s_mov_b64 vcc, s[48:49]
	s_nop 0
	v_cndmask_b32_dpp v140, v111, v127, vcc quad_perm:[1,0,3,2] row_mask:0xf bank_mask:0xf
	v_cndmask_b32_dpp v141, v79, v95, vcc quad_perm:[1,0,3,2] row_mask:0xf bank_mask:0xf
	v_cndmask_b32_dpp v142, v47, v63, vcc quad_perm:[1,0,3,2] row_mask:0xf bank_mask:0xf
	v_cndmask_b32_dpp v143, v15, v31, vcc quad_perm:[1,0,3,2] row_mask:0xf bank_mask:0xf
	s_mov_b64 vcc, s[50:51]
	s_nop 0
	v_cndmask_b32_dpp v111, v127, v111, vcc quad_perm:[1,0,3,2] row_mask:0xf bank_mask:0xf
	v_cndmask_b32_dpp v79, v95, v79, vcc quad_perm:[1,0,3,2] row_mask:0xf bank_mask:0xf
	v_cndmask_b32_dpp v47, v63, v47, vcc quad_perm:[1,0,3,2] row_mask:0xf bank_mask:0xf
	v_cndmask_b32_dpp v15, v31, v15, vcc quad_perm:[1,0,3,2] row_mask:0xf bank_mask:0xf
	s_mov_b64 vcc, s[52:53]
	s_nop 0
	v_cndmask_b32_dpp v127, v141, v140, vcc quad_perm:[2,3,0,1] row_mask:0xf bank_mask:0xf
	v_cndmask_b32_dpp v95, v79, v111, vcc quad_perm:[2,3,0,1] row_mask:0xf bank_mask:0xf
	v_cndmask_b32_dpp v63, v143, v142, vcc quad_perm:[2,3,0,1] row_mask:0xf bank_mask:0xf
	v_cndmask_b32_dpp v31, v15, v47, vcc quad_perm:[2,3,0,1] row_mask:0xf bank_mask:0xf
	s_mov_b64 vcc, s[54:55]
	s_nop 0
	v_cndmask_b32_dpp v141, v140, v141, vcc quad_perm:[2,3,0,1] row_mask:0xf bank_mask:0xf
	v_cndmask_b32_dpp v79, v111, v79, vcc quad_perm:[2,3,0,1] row_mask:0xf bank_mask:0xf
	v_cndmask_b32_dpp v143, v142, v143, vcc quad_perm:[2,3,0,1] row_mask:0xf bank_mask:0xf
	v_cndmask_b32_dpp v15, v47, v15, vcc quad_perm:[2,3,0,1] row_mask:0xf bank_mask:0xf
	v_cvt_pk_bf16_f32 v127, v127, v95
	v_cvt_pk_bf16_f32 v111, v141, v79
	v_cvt_pk_bf16_f32 v63, v63, v31
	v_cvt_pk_bf16_f32 v47, v143, v15
	ds_bpermute_b32 v168, v176, v127
	ds_bpermute_b32 v169, v176, v111
	ds_bpermute_b32 v170, v176, v63
	ds_bpermute_b32 v171, v176, v47
	s_waitcnt lgkmcnt(4)
	global_store_dwordx2 v[152:153], v[172:173], off
	global_store_dwordx2 v[152:153], v[174:175], off offset:256
	v_lshl_add_u64 v[186:187], v[152:153], 0, s[20:21]
	s_mov_b64 vcc, s[48:49]
	s_nop 0
	v_cndmask_b32_dpp v140, v112, v128, vcc quad_perm:[1,0,3,2] row_mask:0xf bank_mask:0xf
	v_cndmask_b32_dpp v141, v80, v96, vcc quad_perm:[1,0,3,2] row_mask:0xf bank_mask:0xf
	v_cndmask_b32_dpp v142, v48, v64, vcc quad_perm:[1,0,3,2] row_mask:0xf bank_mask:0xf
	v_cndmask_b32_dpp v143, v16, v32, vcc quad_perm:[1,0,3,2] row_mask:0xf bank_mask:0xf
	s_mov_b64 vcc, s[50:51]
	s_nop 0
	v_cndmask_b32_dpp v112, v128, v112, vcc quad_perm:[1,0,3,2] row_mask:0xf bank_mask:0xf
	v_cndmask_b32_dpp v80, v96, v80, vcc quad_perm:[1,0,3,2] row_mask:0xf bank_mask:0xf
	v_cndmask_b32_dpp v48, v64, v48, vcc quad_perm:[1,0,3,2] row_mask:0xf bank_mask:0xf
	v_cndmask_b32_dpp v16, v32, v16, vcc quad_perm:[1,0,3,2] row_mask:0xf bank_mask:0xf
	s_mov_b64 vcc, s[52:53]
	s_nop 0
	v_cndmask_b32_dpp v128, v141, v140, vcc quad_perm:[2,3,0,1] row_mask:0xf bank_mask:0xf
	v_cndmask_b32_dpp v96, v80, v112, vcc quad_perm:[2,3,0,1] row_mask:0xf bank_mask:0xf
	v_cndmask_b32_dpp v64, v143, v142, vcc quad_perm:[2,3,0,1] row_mask:0xf bank_mask:0xf
	v_cndmask_b32_dpp v32, v16, v48, vcc quad_perm:[2,3,0,1] row_mask:0xf bank_mask:0xf
	s_mov_b64 vcc, s[54:55]
	s_nop 0
	v_cndmask_b32_dpp v141, v140, v141, vcc quad_perm:[2,3,0,1] row_mask:0xf bank_mask:0xf
	v_cndmask_b32_dpp v80, v112, v80, vcc quad_perm:[2,3,0,1] row_mask:0xf bank_mask:0xf
	v_cndmask_b32_dpp v143, v142, v143, vcc quad_perm:[2,3,0,1] row_mask:0xf bank_mask:0xf
	v_cndmask_b32_dpp v16, v48, v16, vcc quad_perm:[2,3,0,1] row_mask:0xf bank_mask:0xf
	v_cvt_pk_bf16_f32 v128, v128, v96
	v_cvt_pk_bf16_f32 v112, v141, v80
	v_cvt_pk_bf16_f32 v64, v64, v32
	v_cvt_pk_bf16_f32 v48, v143, v16
	ds_bpermute_b32 v172, v176, v128
	ds_bpermute_b32 v173, v176, v112
	ds_bpermute_b32 v174, v176, v64
	ds_bpermute_b32 v175, v176, v48
	s_waitcnt lgkmcnt(4)
	global_store_dwordx2 v[188:189], v[168:169], off
	global_store_dwordx2 v[188:189], v[170:171], off offset:256
	v_lshl_add_u64 v[188:189], v[152:153], 0, s[60:61]
	s_mov_b64 vcc, s[48:49]
	s_nop 0
	v_cndmask_b32_dpp v140, v113, v129, vcc quad_perm:[1,0,3,2] row_mask:0xf bank_mask:0xf
	v_cndmask_b32_dpp v141, v81, v97, vcc quad_perm:[1,0,3,2] row_mask:0xf bank_mask:0xf
	v_cndmask_b32_dpp v142, v49, v65, vcc quad_perm:[1,0,3,2] row_mask:0xf bank_mask:0xf
	v_cndmask_b32_dpp v143, v17, v33, vcc quad_perm:[1,0,3,2] row_mask:0xf bank_mask:0xf
	s_mov_b64 vcc, s[50:51]
	s_nop 0
	v_cndmask_b32_dpp v113, v129, v113, vcc quad_perm:[1,0,3,2] row_mask:0xf bank_mask:0xf
	v_cndmask_b32_dpp v81, v97, v81, vcc quad_perm:[1,0,3,2] row_mask:0xf bank_mask:0xf
	v_cndmask_b32_dpp v49, v65, v49, vcc quad_perm:[1,0,3,2] row_mask:0xf bank_mask:0xf
	v_cndmask_b32_dpp v17, v33, v17, vcc quad_perm:[1,0,3,2] row_mask:0xf bank_mask:0xf
	s_mov_b64 vcc, s[52:53]
	s_nop 0
	v_cndmask_b32_dpp v129, v141, v140, vcc quad_perm:[2,3,0,1] row_mask:0xf bank_mask:0xf
	v_cndmask_b32_dpp v97, v81, v113, vcc quad_perm:[2,3,0,1] row_mask:0xf bank_mask:0xf
	v_cndmask_b32_dpp v65, v143, v142, vcc quad_perm:[2,3,0,1] row_mask:0xf bank_mask:0xf
	v_cndmask_b32_dpp v33, v17, v49, vcc quad_perm:[2,3,0,1] row_mask:0xf bank_mask:0xf
	s_mov_b64 vcc, s[54:55]
	s_nop 0
	v_cndmask_b32_dpp v141, v140, v141, vcc quad_perm:[2,3,0,1] row_mask:0xf bank_mask:0xf
	v_cndmask_b32_dpp v81, v113, v81, vcc quad_perm:[2,3,0,1] row_mask:0xf bank_mask:0xf
	v_cndmask_b32_dpp v143, v142, v143, vcc quad_perm:[2,3,0,1] row_mask:0xf bank_mask:0xf
	v_cndmask_b32_dpp v17, v49, v17, vcc quad_perm:[2,3,0,1] row_mask:0xf bank_mask:0xf
	v_cvt_pk_bf16_f32 v129, v129, v97
	v_cvt_pk_bf16_f32 v113, v141, v81
	v_cvt_pk_bf16_f32 v65, v65, v33
	v_cvt_pk_bf16_f32 v49, v143, v17
	ds_bpermute_b32 v168, v176, v129
	ds_bpermute_b32 v169, v176, v113
	ds_bpermute_b32 v170, v176, v65
	ds_bpermute_b32 v171, v176, v49
	s_waitcnt lgkmcnt(4)
	global_store_dwordx2 v[186:187], v[172:173], off
	global_store_dwordx2 v[186:187], v[174:175], off offset:256
	s_mov_b64 vcc, s[48:49]
	s_nop 0
	v_cndmask_b32_dpp v140, v106, v122, vcc quad_perm:[1,0,3,2] row_mask:0xf bank_mask:0xf
	v_cndmask_b32_dpp v141, v74, v90, vcc quad_perm:[1,0,3,2] row_mask:0xf bank_mask:0xf
	v_cndmask_b32_dpp v142, v42, v58, vcc quad_perm:[1,0,3,2] row_mask:0xf bank_mask:0xf
	v_cndmask_b32_dpp v143, v10, v26, vcc quad_perm:[1,0,3,2] row_mask:0xf bank_mask:0xf
	s_mov_b64 vcc, s[50:51]
	s_nop 0
	v_cndmask_b32_dpp v106, v122, v106, vcc quad_perm:[1,0,3,2] row_mask:0xf bank_mask:0xf
	v_cndmask_b32_dpp v74, v90, v74, vcc quad_perm:[1,0,3,2] row_mask:0xf bank_mask:0xf
	v_cndmask_b32_dpp v42, v58, v42, vcc quad_perm:[1,0,3,2] row_mask:0xf bank_mask:0xf
	v_cndmask_b32_dpp v10, v26, v10, vcc quad_perm:[1,0,3,2] row_mask:0xf bank_mask:0xf
	s_mov_b64 vcc, s[52:53]
	s_nop 0
	v_cndmask_b32_dpp v122, v141, v140, vcc quad_perm:[2,3,0,1] row_mask:0xf bank_mask:0xf
	v_cndmask_b32_dpp v90, v74, v106, vcc quad_perm:[2,3,0,1] row_mask:0xf bank_mask:0xf
	v_cndmask_b32_dpp v58, v143, v142, vcc quad_perm:[2,3,0,1] row_mask:0xf bank_mask:0xf
	v_cndmask_b32_dpp v26, v10, v42, vcc quad_perm:[2,3,0,1] row_mask:0xf bank_mask:0xf
	s_mov_b64 vcc, s[54:55]
	s_nop 0
	v_cndmask_b32_dpp v141, v140, v141, vcc quad_perm:[2,3,0,1] row_mask:0xf bank_mask:0xf
	v_cndmask_b32_dpp v74, v106, v74, vcc quad_perm:[2,3,0,1] row_mask:0xf bank_mask:0xf
	v_cndmask_b32_dpp v143, v142, v143, vcc quad_perm:[2,3,0,1] row_mask:0xf bank_mask:0xf
	v_cndmask_b32_dpp v10, v42, v10, vcc quad_perm:[2,3,0,1] row_mask:0xf bank_mask:0xf
	v_cvt_pk_bf16_f32 v122, v122, v90
	v_cvt_pk_bf16_f32 v106, v141, v74
	v_cvt_pk_bf16_f32 v58, v58, v26
	v_cvt_pk_bf16_f32 v42, v143, v10
	ds_bpermute_b32 v172, v176, v122
	ds_bpermute_b32 v173, v176, v106
	ds_bpermute_b32 v174, v176, v58
	ds_bpermute_b32 v175, v176, v42
	s_waitcnt lgkmcnt(4)
	global_store_dwordx2 v[188:189], v[168:169], off
	global_store_dwordx2 v[188:189], v[170:171], off offset:256
	v_lshl_add_u64 v[188:189], v[162:163], 0, s[0:1]
	s_mov_b64 vcc, s[48:49]
	s_nop 0
	v_cndmask_b32_dpp v140, v107, v123, vcc quad_perm:[1,0,3,2] row_mask:0xf bank_mask:0xf
	v_cndmask_b32_dpp v141, v75, v91, vcc quad_perm:[1,0,3,2] row_mask:0xf bank_mask:0xf
	v_cndmask_b32_dpp v142, v43, v59, vcc quad_perm:[1,0,3,2] row_mask:0xf bank_mask:0xf
	v_cndmask_b32_dpp v143, v11, v27, vcc quad_perm:[1,0,3,2] row_mask:0xf bank_mask:0xf
	s_mov_b64 vcc, s[50:51]
	s_nop 0
	v_cndmask_b32_dpp v107, v123, v107, vcc quad_perm:[1,0,3,2] row_mask:0xf bank_mask:0xf
	v_cndmask_b32_dpp v75, v91, v75, vcc quad_perm:[1,0,3,2] row_mask:0xf bank_mask:0xf
	v_cndmask_b32_dpp v43, v59, v43, vcc quad_perm:[1,0,3,2] row_mask:0xf bank_mask:0xf
	v_cndmask_b32_dpp v11, v27, v11, vcc quad_perm:[1,0,3,2] row_mask:0xf bank_mask:0xf
	s_mov_b64 vcc, s[52:53]
	s_nop 0
	v_cndmask_b32_dpp v123, v141, v140, vcc quad_perm:[2,3,0,1] row_mask:0xf bank_mask:0xf
	v_cndmask_b32_dpp v91, v75, v107, vcc quad_perm:[2,3,0,1] row_mask:0xf bank_mask:0xf
	v_cndmask_b32_dpp v59, v143, v142, vcc quad_perm:[2,3,0,1] row_mask:0xf bank_mask:0xf
	v_cndmask_b32_dpp v27, v11, v43, vcc quad_perm:[2,3,0,1] row_mask:0xf bank_mask:0xf
	s_mov_b64 vcc, s[54:55]
	s_nop 0
	v_cndmask_b32_dpp v141, v140, v141, vcc quad_perm:[2,3,0,1] row_mask:0xf bank_mask:0xf
	v_cndmask_b32_dpp v75, v107, v75, vcc quad_perm:[2,3,0,1] row_mask:0xf bank_mask:0xf
	v_cndmask_b32_dpp v143, v142, v143, vcc quad_perm:[2,3,0,1] row_mask:0xf bank_mask:0xf
	v_cndmask_b32_dpp v11, v43, v11, vcc quad_perm:[2,3,0,1] row_mask:0xf bank_mask:0xf
	v_cvt_pk_bf16_f32 v123, v123, v91
	v_cvt_pk_bf16_f32 v107, v141, v75
	v_cvt_pk_bf16_f32 v59, v59, v27
	v_cvt_pk_bf16_f32 v43, v143, v11
	ds_bpermute_b32 v168, v176, v123
	ds_bpermute_b32 v169, v176, v107
	ds_bpermute_b32 v170, v176, v59
	ds_bpermute_b32 v171, v176, v43
	s_waitcnt lgkmcnt(4)
	global_store_dwordx2 v[162:163], v[172:173], off
	global_store_dwordx2 v[162:163], v[174:175], off offset:256
	v_lshl_add_u64 v[186:187], v[162:163], 0, s[20:21]
	s_mov_b64 vcc, s[48:49]
	s_nop 0
	v_cndmask_b32_dpp v140, v108, v124, vcc quad_perm:[1,0,3,2] row_mask:0xf bank_mask:0xf
	v_cndmask_b32_dpp v141, v76, v92, vcc quad_perm:[1,0,3,2] row_mask:0xf bank_mask:0xf
	v_cndmask_b32_dpp v142, v44, v60, vcc quad_perm:[1,0,3,2] row_mask:0xf bank_mask:0xf
	v_cndmask_b32_dpp v143, v12, v28, vcc quad_perm:[1,0,3,2] row_mask:0xf bank_mask:0xf
	s_mov_b64 vcc, s[50:51]
	s_nop 0
	v_cndmask_b32_dpp v108, v124, v108, vcc quad_perm:[1,0,3,2] row_mask:0xf bank_mask:0xf
	v_cndmask_b32_dpp v76, v92, v76, vcc quad_perm:[1,0,3,2] row_mask:0xf bank_mask:0xf
	v_cndmask_b32_dpp v44, v60, v44, vcc quad_perm:[1,0,3,2] row_mask:0xf bank_mask:0xf
	v_cndmask_b32_dpp v12, v28, v12, vcc quad_perm:[1,0,3,2] row_mask:0xf bank_mask:0xf
	s_mov_b64 vcc, s[52:53]
	s_nop 0
	v_cndmask_b32_dpp v124, v141, v140, vcc quad_perm:[2,3,0,1] row_mask:0xf bank_mask:0xf
	v_cndmask_b32_dpp v92, v76, v108, vcc quad_perm:[2,3,0,1] row_mask:0xf bank_mask:0xf
	v_cndmask_b32_dpp v60, v143, v142, vcc quad_perm:[2,3,0,1] row_mask:0xf bank_mask:0xf
	v_cndmask_b32_dpp v28, v12, v44, vcc quad_perm:[2,3,0,1] row_mask:0xf bank_mask:0xf
	s_mov_b64 vcc, s[54:55]
	s_nop 0
	v_cndmask_b32_dpp v141, v140, v141, vcc quad_perm:[2,3,0,1] row_mask:0xf bank_mask:0xf
	v_cndmask_b32_dpp v76, v108, v76, vcc quad_perm:[2,3,0,1] row_mask:0xf bank_mask:0xf
	v_cndmask_b32_dpp v143, v142, v143, vcc quad_perm:[2,3,0,1] row_mask:0xf bank_mask:0xf
	v_cndmask_b32_dpp v12, v44, v12, vcc quad_perm:[2,3,0,1] row_mask:0xf bank_mask:0xf
	v_cvt_pk_bf16_f32 v124, v124, v92
	v_cvt_pk_bf16_f32 v108, v141, v76
	v_cvt_pk_bf16_f32 v60, v60, v28
	v_cvt_pk_bf16_f32 v44, v143, v12
	ds_bpermute_b32 v172, v176, v124
	ds_bpermute_b32 v173, v176, v108
	ds_bpermute_b32 v174, v176, v60
	ds_bpermute_b32 v175, v176, v44
	s_waitcnt lgkmcnt(4)
	global_store_dwordx2 v[188:189], v[168:169], off
	global_store_dwordx2 v[188:189], v[170:171], off offset:256
	v_lshl_add_u64 v[188:189], v[162:163], 0, s[60:61]
	s_mov_b64 vcc, s[48:49]
	s_nop 0
	v_cndmask_b32_dpp v140, v109, v125, vcc quad_perm:[1,0,3,2] row_mask:0xf bank_mask:0xf
	v_cndmask_b32_dpp v141, v77, v93, vcc quad_perm:[1,0,3,2] row_mask:0xf bank_mask:0xf
	v_cndmask_b32_dpp v142, v45, v61, vcc quad_perm:[1,0,3,2] row_mask:0xf bank_mask:0xf
	v_cndmask_b32_dpp v143, v13, v29, vcc quad_perm:[1,0,3,2] row_mask:0xf bank_mask:0xf
	s_mov_b64 vcc, s[50:51]
	s_nop 0
	v_cndmask_b32_dpp v109, v125, v109, vcc quad_perm:[1,0,3,2] row_mask:0xf bank_mask:0xf
	v_cndmask_b32_dpp v77, v93, v77, vcc quad_perm:[1,0,3,2] row_mask:0xf bank_mask:0xf
	v_cndmask_b32_dpp v45, v61, v45, vcc quad_perm:[1,0,3,2] row_mask:0xf bank_mask:0xf
	v_cndmask_b32_dpp v13, v29, v13, vcc quad_perm:[1,0,3,2] row_mask:0xf bank_mask:0xf
	s_mov_b64 vcc, s[52:53]
	s_nop 0
	v_cndmask_b32_dpp v125, v141, v140, vcc quad_perm:[2,3,0,1] row_mask:0xf bank_mask:0xf
	v_cndmask_b32_dpp v93, v77, v109, vcc quad_perm:[2,3,0,1] row_mask:0xf bank_mask:0xf
	v_cndmask_b32_dpp v61, v143, v142, vcc quad_perm:[2,3,0,1] row_mask:0xf bank_mask:0xf
	v_cndmask_b32_dpp v29, v13, v45, vcc quad_perm:[2,3,0,1] row_mask:0xf bank_mask:0xf
	s_mov_b64 vcc, s[54:55]
	s_nop 0
	v_cndmask_b32_dpp v141, v140, v141, vcc quad_perm:[2,3,0,1] row_mask:0xf bank_mask:0xf
	v_cndmask_b32_dpp v77, v109, v77, vcc quad_perm:[2,3,0,1] row_mask:0xf bank_mask:0xf
	v_cndmask_b32_dpp v143, v142, v143, vcc quad_perm:[2,3,0,1] row_mask:0xf bank_mask:0xf
	v_cndmask_b32_dpp v13, v45, v13, vcc quad_perm:[2,3,0,1] row_mask:0xf bank_mask:0xf
	v_cvt_pk_bf16_f32 v125, v125, v93
	v_cvt_pk_bf16_f32 v109, v141, v77
	v_cvt_pk_bf16_f32 v61, v61, v29
	v_cvt_pk_bf16_f32 v45, v143, v13
	ds_bpermute_b32 v168, v176, v125
	ds_bpermute_b32 v169, v176, v109
	ds_bpermute_b32 v170, v176, v61
	ds_bpermute_b32 v171, v176, v45
	s_waitcnt lgkmcnt(4)
	global_store_dwordx2 v[186:187], v[172:173], off
	global_store_dwordx2 v[186:187], v[174:175], off offset:256
	s_mov_b64 vcc, s[48:49]
	s_nop 0
	v_cndmask_b32_dpp v140, v102, v118, vcc quad_perm:[1,0,3,2] row_mask:0xf bank_mask:0xf
	v_cndmask_b32_dpp v141, v70, v86, vcc quad_perm:[1,0,3,2] row_mask:0xf bank_mask:0xf
	v_cndmask_b32_dpp v142, v38, v54, vcc quad_perm:[1,0,3,2] row_mask:0xf bank_mask:0xf
	v_cndmask_b32_dpp v143, v6, v22, vcc quad_perm:[1,0,3,2] row_mask:0xf bank_mask:0xf
	s_mov_b64 vcc, s[50:51]
	s_nop 0
	v_cndmask_b32_dpp v102, v118, v102, vcc quad_perm:[1,0,3,2] row_mask:0xf bank_mask:0xf
	v_cndmask_b32_dpp v70, v86, v70, vcc quad_perm:[1,0,3,2] row_mask:0xf bank_mask:0xf
	v_cndmask_b32_dpp v38, v54, v38, vcc quad_perm:[1,0,3,2] row_mask:0xf bank_mask:0xf
	v_cndmask_b32_dpp v6, v22, v6, vcc quad_perm:[1,0,3,2] row_mask:0xf bank_mask:0xf
	s_mov_b64 vcc, s[52:53]
	s_nop 0
	v_cndmask_b32_dpp v118, v141, v140, vcc quad_perm:[2,3,0,1] row_mask:0xf bank_mask:0xf
	v_cndmask_b32_dpp v86, v70, v102, vcc quad_perm:[2,3,0,1] row_mask:0xf bank_mask:0xf
	v_cndmask_b32_dpp v54, v143, v142, vcc quad_perm:[2,3,0,1] row_mask:0xf bank_mask:0xf
	v_cndmask_b32_dpp v22, v6, v38, vcc quad_perm:[2,3,0,1] row_mask:0xf bank_mask:0xf
	s_mov_b64 vcc, s[54:55]
	s_nop 0
	v_cndmask_b32_dpp v141, v140, v141, vcc quad_perm:[2,3,0,1] row_mask:0xf bank_mask:0xf
	v_cndmask_b32_dpp v70, v102, v70, vcc quad_perm:[2,3,0,1] row_mask:0xf bank_mask:0xf
	v_cndmask_b32_dpp v143, v142, v143, vcc quad_perm:[2,3,0,1] row_mask:0xf bank_mask:0xf
	v_cndmask_b32_dpp v6, v38, v6, vcc quad_perm:[2,3,0,1] row_mask:0xf bank_mask:0xf
	v_cvt_pk_bf16_f32 v118, v118, v86
	v_cvt_pk_bf16_f32 v102, v141, v70
	v_cvt_pk_bf16_f32 v54, v54, v22
	v_cvt_pk_bf16_f32 v38, v143, v6
	ds_bpermute_b32 v172, v176, v118
	ds_bpermute_b32 v173, v176, v102
	ds_bpermute_b32 v174, v176, v54
	ds_bpermute_b32 v175, v176, v38
	s_waitcnt lgkmcnt(4)
	global_store_dwordx2 v[188:189], v[168:169], off
	global_store_dwordx2 v[188:189], v[170:171], off offset:256
	v_lshl_add_u64 v[188:189], v[164:165], 0, s[0:1]
	s_mov_b64 vcc, s[48:49]
	s_nop 0
	v_cndmask_b32_dpp v140, v103, v119, vcc quad_perm:[1,0,3,2] row_mask:0xf bank_mask:0xf
	v_cndmask_b32_dpp v141, v71, v87, vcc quad_perm:[1,0,3,2] row_mask:0xf bank_mask:0xf
	v_cndmask_b32_dpp v142, v39, v55, vcc quad_perm:[1,0,3,2] row_mask:0xf bank_mask:0xf
	v_cndmask_b32_dpp v143, v7, v23, vcc quad_perm:[1,0,3,2] row_mask:0xf bank_mask:0xf
	s_mov_b64 vcc, s[50:51]
	s_nop 0
	v_cndmask_b32_dpp v103, v119, v103, vcc quad_perm:[1,0,3,2] row_mask:0xf bank_mask:0xf
	v_cndmask_b32_dpp v71, v87, v71, vcc quad_perm:[1,0,3,2] row_mask:0xf bank_mask:0xf
	v_cndmask_b32_dpp v39, v55, v39, vcc quad_perm:[1,0,3,2] row_mask:0xf bank_mask:0xf
	v_cndmask_b32_dpp v7, v23, v7, vcc quad_perm:[1,0,3,2] row_mask:0xf bank_mask:0xf
	s_mov_b64 vcc, s[52:53]
	s_nop 0
	v_cndmask_b32_dpp v119, v141, v140, vcc quad_perm:[2,3,0,1] row_mask:0xf bank_mask:0xf
	v_cndmask_b32_dpp v87, v71, v103, vcc quad_perm:[2,3,0,1] row_mask:0xf bank_mask:0xf
	v_cndmask_b32_dpp v55, v143, v142, vcc quad_perm:[2,3,0,1] row_mask:0xf bank_mask:0xf
	v_cndmask_b32_dpp v23, v7, v39, vcc quad_perm:[2,3,0,1] row_mask:0xf bank_mask:0xf
	s_mov_b64 vcc, s[54:55]
	s_nop 0
	v_cndmask_b32_dpp v141, v140, v141, vcc quad_perm:[2,3,0,1] row_mask:0xf bank_mask:0xf
	v_cndmask_b32_dpp v71, v103, v71, vcc quad_perm:[2,3,0,1] row_mask:0xf bank_mask:0xf
	v_cndmask_b32_dpp v143, v142, v143, vcc quad_perm:[2,3,0,1] row_mask:0xf bank_mask:0xf
	v_cndmask_b32_dpp v7, v39, v7, vcc quad_perm:[2,3,0,1] row_mask:0xf bank_mask:0xf
	v_cvt_pk_bf16_f32 v119, v119, v87
	v_cvt_pk_bf16_f32 v103, v141, v71
	v_cvt_pk_bf16_f32 v55, v55, v23
	v_cvt_pk_bf16_f32 v39, v143, v7
	ds_bpermute_b32 v168, v176, v119
	ds_bpermute_b32 v169, v176, v103
	ds_bpermute_b32 v170, v176, v55
	ds_bpermute_b32 v171, v176, v39
	s_waitcnt lgkmcnt(4)
	global_store_dwordx2 v[164:165], v[172:173], off
	global_store_dwordx2 v[164:165], v[174:175], off offset:256
	v_lshl_add_u64 v[186:187], v[164:165], 0, s[20:21]
	s_mov_b64 vcc, s[48:49]
	s_nop 0
	v_cndmask_b32_dpp v140, v104, v120, vcc quad_perm:[1,0,3,2] row_mask:0xf bank_mask:0xf
	v_cndmask_b32_dpp v141, v72, v88, vcc quad_perm:[1,0,3,2] row_mask:0xf bank_mask:0xf
	v_cndmask_b32_dpp v142, v40, v56, vcc quad_perm:[1,0,3,2] row_mask:0xf bank_mask:0xf
	v_cndmask_b32_dpp v143, v8, v24, vcc quad_perm:[1,0,3,2] row_mask:0xf bank_mask:0xf
	s_mov_b64 vcc, s[50:51]
	s_nop 0
	v_cndmask_b32_dpp v104, v120, v104, vcc quad_perm:[1,0,3,2] row_mask:0xf bank_mask:0xf
	v_cndmask_b32_dpp v72, v88, v72, vcc quad_perm:[1,0,3,2] row_mask:0xf bank_mask:0xf
	v_cndmask_b32_dpp v40, v56, v40, vcc quad_perm:[1,0,3,2] row_mask:0xf bank_mask:0xf
	v_cndmask_b32_dpp v8, v24, v8, vcc quad_perm:[1,0,3,2] row_mask:0xf bank_mask:0xf
	s_mov_b64 vcc, s[52:53]
	s_nop 0
	v_cndmask_b32_dpp v120, v141, v140, vcc quad_perm:[2,3,0,1] row_mask:0xf bank_mask:0xf
	v_cndmask_b32_dpp v88, v72, v104, vcc quad_perm:[2,3,0,1] row_mask:0xf bank_mask:0xf
	v_cndmask_b32_dpp v56, v143, v142, vcc quad_perm:[2,3,0,1] row_mask:0xf bank_mask:0xf
	v_cndmask_b32_dpp v24, v8, v40, vcc quad_perm:[2,3,0,1] row_mask:0xf bank_mask:0xf
	s_mov_b64 vcc, s[54:55]
	s_nop 0
	v_cndmask_b32_dpp v141, v140, v141, vcc quad_perm:[2,3,0,1] row_mask:0xf bank_mask:0xf
	v_cndmask_b32_dpp v72, v104, v72, vcc quad_perm:[2,3,0,1] row_mask:0xf bank_mask:0xf
	v_cndmask_b32_dpp v143, v142, v143, vcc quad_perm:[2,3,0,1] row_mask:0xf bank_mask:0xf
	v_cndmask_b32_dpp v8, v40, v8, vcc quad_perm:[2,3,0,1] row_mask:0xf bank_mask:0xf
	v_cvt_pk_bf16_f32 v120, v120, v88
	v_cvt_pk_bf16_f32 v104, v141, v72
	v_cvt_pk_bf16_f32 v56, v56, v24
	v_cvt_pk_bf16_f32 v40, v143, v8
	ds_bpermute_b32 v172, v176, v120
	ds_bpermute_b32 v173, v176, v104
	ds_bpermute_b32 v174, v176, v56
	ds_bpermute_b32 v175, v176, v40
	s_waitcnt lgkmcnt(4)
	global_store_dwordx2 v[188:189], v[168:169], off
	global_store_dwordx2 v[188:189], v[170:171], off offset:256
	v_lshl_add_u64 v[188:189], v[164:165], 0, s[60:61]
	s_mov_b64 vcc, s[48:49]
	s_nop 0
	v_cndmask_b32_dpp v140, v105, v121, vcc quad_perm:[1,0,3,2] row_mask:0xf bank_mask:0xf
	v_cndmask_b32_dpp v141, v73, v89, vcc quad_perm:[1,0,3,2] row_mask:0xf bank_mask:0xf
	v_cndmask_b32_dpp v142, v41, v57, vcc quad_perm:[1,0,3,2] row_mask:0xf bank_mask:0xf
	v_cndmask_b32_dpp v143, v9, v25, vcc quad_perm:[1,0,3,2] row_mask:0xf bank_mask:0xf
	s_mov_b64 vcc, s[50:51]
	s_nop 0
	v_cndmask_b32_dpp v105, v121, v105, vcc quad_perm:[1,0,3,2] row_mask:0xf bank_mask:0xf
	v_cndmask_b32_dpp v73, v89, v73, vcc quad_perm:[1,0,3,2] row_mask:0xf bank_mask:0xf
	v_cndmask_b32_dpp v41, v57, v41, vcc quad_perm:[1,0,3,2] row_mask:0xf bank_mask:0xf
	v_cndmask_b32_dpp v9, v25, v9, vcc quad_perm:[1,0,3,2] row_mask:0xf bank_mask:0xf
	s_mov_b64 vcc, s[52:53]
	s_nop 0
	v_cndmask_b32_dpp v121, v141, v140, vcc quad_perm:[2,3,0,1] row_mask:0xf bank_mask:0xf
	v_cndmask_b32_dpp v89, v73, v105, vcc quad_perm:[2,3,0,1] row_mask:0xf bank_mask:0xf
	v_cndmask_b32_dpp v57, v143, v142, vcc quad_perm:[2,3,0,1] row_mask:0xf bank_mask:0xf
	v_cndmask_b32_dpp v25, v9, v41, vcc quad_perm:[2,3,0,1] row_mask:0xf bank_mask:0xf
	s_mov_b64 vcc, s[54:55]
	s_nop 0
	v_cndmask_b32_dpp v141, v140, v141, vcc quad_perm:[2,3,0,1] row_mask:0xf bank_mask:0xf
	v_cndmask_b32_dpp v73, v105, v73, vcc quad_perm:[2,3,0,1] row_mask:0xf bank_mask:0xf
	v_cndmask_b32_dpp v143, v142, v143, vcc quad_perm:[2,3,0,1] row_mask:0xf bank_mask:0xf
	v_cndmask_b32_dpp v9, v41, v9, vcc quad_perm:[2,3,0,1] row_mask:0xf bank_mask:0xf
	v_cvt_pk_bf16_f32 v121, v121, v89
	v_cvt_pk_bf16_f32 v105, v141, v73
	v_cvt_pk_bf16_f32 v57, v57, v25
	v_cvt_pk_bf16_f32 v41, v143, v9
	ds_bpermute_b32 v168, v176, v121
	ds_bpermute_b32 v169, v176, v105
	ds_bpermute_b32 v170, v176, v57
	ds_bpermute_b32 v171, v176, v41
	s_waitcnt lgkmcnt(4)
	global_store_dwordx2 v[186:187], v[172:173], off
	global_store_dwordx2 v[186:187], v[174:175], off offset:256
	s_mov_b64 vcc, s[48:49]
	s_nop 0
	v_cndmask_b32_dpp v140, v98, v114, vcc quad_perm:[1,0,3,2] row_mask:0xf bank_mask:0xf
	v_cndmask_b32_dpp v141, v66, v82, vcc quad_perm:[1,0,3,2] row_mask:0xf bank_mask:0xf
	v_cndmask_b32_dpp v142, v34, v50, vcc quad_perm:[1,0,3,2] row_mask:0xf bank_mask:0xf
	v_cndmask_b32_dpp v143, v2, v18, vcc quad_perm:[1,0,3,2] row_mask:0xf bank_mask:0xf
	s_mov_b64 vcc, s[50:51]
	s_nop 0
	v_cndmask_b32_dpp v98, v114, v98, vcc quad_perm:[1,0,3,2] row_mask:0xf bank_mask:0xf
	v_cndmask_b32_dpp v66, v82, v66, vcc quad_perm:[1,0,3,2] row_mask:0xf bank_mask:0xf
	v_cndmask_b32_dpp v34, v50, v34, vcc quad_perm:[1,0,3,2] row_mask:0xf bank_mask:0xf
	v_cndmask_b32_dpp v2, v18, v2, vcc quad_perm:[1,0,3,2] row_mask:0xf bank_mask:0xf
	s_mov_b64 vcc, s[52:53]
	s_nop 0
	v_cndmask_b32_dpp v114, v141, v140, vcc quad_perm:[2,3,0,1] row_mask:0xf bank_mask:0xf
	v_cndmask_b32_dpp v82, v66, v98, vcc quad_perm:[2,3,0,1] row_mask:0xf bank_mask:0xf
	v_cndmask_b32_dpp v50, v143, v142, vcc quad_perm:[2,3,0,1] row_mask:0xf bank_mask:0xf
	v_cndmask_b32_dpp v18, v2, v34, vcc quad_perm:[2,3,0,1] row_mask:0xf bank_mask:0xf
	s_mov_b64 vcc, s[54:55]
	s_nop 0
	v_cndmask_b32_dpp v141, v140, v141, vcc quad_perm:[2,3,0,1] row_mask:0xf bank_mask:0xf
	v_cndmask_b32_dpp v66, v98, v66, vcc quad_perm:[2,3,0,1] row_mask:0xf bank_mask:0xf
	v_cndmask_b32_dpp v143, v142, v143, vcc quad_perm:[2,3,0,1] row_mask:0xf bank_mask:0xf
	v_cndmask_b32_dpp v2, v34, v2, vcc quad_perm:[2,3,0,1] row_mask:0xf bank_mask:0xf
	v_cvt_pk_bf16_f32 v114, v114, v82
	v_cvt_pk_bf16_f32 v98, v141, v66
	v_cvt_pk_bf16_f32 v50, v50, v18
	v_cvt_pk_bf16_f32 v34, v143, v2
	ds_bpermute_b32 v172, v176, v114
	ds_bpermute_b32 v173, v176, v98
	ds_bpermute_b32 v174, v176, v50
	ds_bpermute_b32 v175, v176, v34
	s_waitcnt lgkmcnt(4)
	global_store_dwordx2 v[188:189], v[168:169], off
	global_store_dwordx2 v[188:189], v[170:171], off offset:256
	v_lshl_add_u64 v[188:189], v[166:167], 0, s[0:1]
	s_mov_b64 vcc, s[48:49]
	s_nop 0
	v_cndmask_b32_dpp v140, v99, v115, vcc quad_perm:[1,0,3,2] row_mask:0xf bank_mask:0xf
	v_cndmask_b32_dpp v141, v67, v83, vcc quad_perm:[1,0,3,2] row_mask:0xf bank_mask:0xf
	v_cndmask_b32_dpp v142, v35, v51, vcc quad_perm:[1,0,3,2] row_mask:0xf bank_mask:0xf
	v_cndmask_b32_dpp v143, v3, v19, vcc quad_perm:[1,0,3,2] row_mask:0xf bank_mask:0xf
	s_mov_b64 vcc, s[50:51]
	s_nop 0
	v_cndmask_b32_dpp v99, v115, v99, vcc quad_perm:[1,0,3,2] row_mask:0xf bank_mask:0xf
	v_cndmask_b32_dpp v67, v83, v67, vcc quad_perm:[1,0,3,2] row_mask:0xf bank_mask:0xf
	v_cndmask_b32_dpp v35, v51, v35, vcc quad_perm:[1,0,3,2] row_mask:0xf bank_mask:0xf
	v_cndmask_b32_dpp v3, v19, v3, vcc quad_perm:[1,0,3,2] row_mask:0xf bank_mask:0xf
	s_mov_b64 vcc, s[52:53]
	s_nop 0
	v_cndmask_b32_dpp v115, v141, v140, vcc quad_perm:[2,3,0,1] row_mask:0xf bank_mask:0xf
	v_cndmask_b32_dpp v83, v67, v99, vcc quad_perm:[2,3,0,1] row_mask:0xf bank_mask:0xf
	v_cndmask_b32_dpp v51, v143, v142, vcc quad_perm:[2,3,0,1] row_mask:0xf bank_mask:0xf
	v_cndmask_b32_dpp v19, v3, v35, vcc quad_perm:[2,3,0,1] row_mask:0xf bank_mask:0xf
	s_mov_b64 vcc, s[54:55]
	s_nop 0
	v_cndmask_b32_dpp v141, v140, v141, vcc quad_perm:[2,3,0,1] row_mask:0xf bank_mask:0xf
	v_cndmask_b32_dpp v67, v99, v67, vcc quad_perm:[2,3,0,1] row_mask:0xf bank_mask:0xf
	v_cndmask_b32_dpp v143, v142, v143, vcc quad_perm:[2,3,0,1] row_mask:0xf bank_mask:0xf
	v_cndmask_b32_dpp v3, v35, v3, vcc quad_perm:[2,3,0,1] row_mask:0xf bank_mask:0xf
	v_cvt_pk_bf16_f32 v115, v115, v83
	v_cvt_pk_bf16_f32 v99, v141, v67
	v_cvt_pk_bf16_f32 v51, v51, v19
	v_cvt_pk_bf16_f32 v35, v143, v3
	ds_bpermute_b32 v168, v176, v115
	ds_bpermute_b32 v169, v176, v99
	ds_bpermute_b32 v170, v176, v51
	ds_bpermute_b32 v171, v176, v35
	s_waitcnt lgkmcnt(4)
	global_store_dwordx2 v[166:167], v[172:173], off
	global_store_dwordx2 v[166:167], v[174:175], off offset:256
	v_lshl_add_u64 v[186:187], v[166:167], 0, s[20:21]
	s_mov_b64 vcc, s[48:49]
	s_nop 0
	v_cndmask_b32_dpp v140, v100, v116, vcc quad_perm:[1,0,3,2] row_mask:0xf bank_mask:0xf
	v_cndmask_b32_dpp v141, v68, v84, vcc quad_perm:[1,0,3,2] row_mask:0xf bank_mask:0xf
	v_cndmask_b32_dpp v142, v36, v52, vcc quad_perm:[1,0,3,2] row_mask:0xf bank_mask:0xf
	v_cndmask_b32_dpp v143, v4, v20, vcc quad_perm:[1,0,3,2] row_mask:0xf bank_mask:0xf
	s_mov_b64 vcc, s[50:51]
	s_nop 0
	v_cndmask_b32_dpp v100, v116, v100, vcc quad_perm:[1,0,3,2] row_mask:0xf bank_mask:0xf
	v_cndmask_b32_dpp v68, v84, v68, vcc quad_perm:[1,0,3,2] row_mask:0xf bank_mask:0xf
	v_cndmask_b32_dpp v36, v52, v36, vcc quad_perm:[1,0,3,2] row_mask:0xf bank_mask:0xf
	v_cndmask_b32_dpp v4, v20, v4, vcc quad_perm:[1,0,3,2] row_mask:0xf bank_mask:0xf
	s_mov_b64 vcc, s[52:53]
	s_nop 0
	v_cndmask_b32_dpp v116, v141, v140, vcc quad_perm:[2,3,0,1] row_mask:0xf bank_mask:0xf
	v_cndmask_b32_dpp v84, v68, v100, vcc quad_perm:[2,3,0,1] row_mask:0xf bank_mask:0xf
	v_cndmask_b32_dpp v52, v143, v142, vcc quad_perm:[2,3,0,1] row_mask:0xf bank_mask:0xf
	v_cndmask_b32_dpp v20, v4, v36, vcc quad_perm:[2,3,0,1] row_mask:0xf bank_mask:0xf
	s_mov_b64 vcc, s[54:55]
	s_nop 0
	v_cndmask_b32_dpp v141, v140, v141, vcc quad_perm:[2,3,0,1] row_mask:0xf bank_mask:0xf
	v_cndmask_b32_dpp v68, v100, v68, vcc quad_perm:[2,3,0,1] row_mask:0xf bank_mask:0xf
	v_cndmask_b32_dpp v143, v142, v143, vcc quad_perm:[2,3,0,1] row_mask:0xf bank_mask:0xf
	v_cndmask_b32_dpp v4, v36, v4, vcc quad_perm:[2,3,0,1] row_mask:0xf bank_mask:0xf
	v_cvt_pk_bf16_f32 v116, v116, v84
	v_cvt_pk_bf16_f32 v100, v141, v68
	v_cvt_pk_bf16_f32 v52, v52, v20
	v_cvt_pk_bf16_f32 v36, v143, v4
	ds_bpermute_b32 v172, v176, v116
	ds_bpermute_b32 v173, v176, v100
	ds_bpermute_b32 v174, v176, v52
	ds_bpermute_b32 v175, v176, v36
	s_waitcnt lgkmcnt(4)
	global_store_dwordx2 v[188:189], v[168:169], off
	global_store_dwordx2 v[188:189], v[170:171], off offset:256
	v_lshl_add_u64 v[188:189], v[166:167], 0, s[60:61]
	s_mov_b64 vcc, s[48:49]
	s_nop 0
	v_cndmask_b32_dpp v140, v101, v117, vcc quad_perm:[1,0,3,2] row_mask:0xf bank_mask:0xf
	v_cndmask_b32_dpp v141, v69, v85, vcc quad_perm:[1,0,3,2] row_mask:0xf bank_mask:0xf
	v_cndmask_b32_dpp v142, v37, v53, vcc quad_perm:[1,0,3,2] row_mask:0xf bank_mask:0xf
	v_cndmask_b32_dpp v143, v5, v21, vcc quad_perm:[1,0,3,2] row_mask:0xf bank_mask:0xf
	s_mov_b64 vcc, s[50:51]
	s_nop 0
	v_cndmask_b32_dpp v101, v117, v101, vcc quad_perm:[1,0,3,2] row_mask:0xf bank_mask:0xf
	v_cndmask_b32_dpp v69, v85, v69, vcc quad_perm:[1,0,3,2] row_mask:0xf bank_mask:0xf
	v_cndmask_b32_dpp v37, v53, v37, vcc quad_perm:[1,0,3,2] row_mask:0xf bank_mask:0xf
	v_cndmask_b32_dpp v5, v21, v5, vcc quad_perm:[1,0,3,2] row_mask:0xf bank_mask:0xf
	s_mov_b64 vcc, s[52:53]
	s_nop 0
	v_cndmask_b32_dpp v117, v141, v140, vcc quad_perm:[2,3,0,1] row_mask:0xf bank_mask:0xf
	v_cndmask_b32_dpp v85, v69, v101, vcc quad_perm:[2,3,0,1] row_mask:0xf bank_mask:0xf
	v_cndmask_b32_dpp v53, v143, v142, vcc quad_perm:[2,3,0,1] row_mask:0xf bank_mask:0xf
	v_cndmask_b32_dpp v21, v5, v37, vcc quad_perm:[2,3,0,1] row_mask:0xf bank_mask:0xf
	s_mov_b64 vcc, s[54:55]
	s_nop 0
	v_cndmask_b32_dpp v141, v140, v141, vcc quad_perm:[2,3,0,1] row_mask:0xf bank_mask:0xf
	v_cndmask_b32_dpp v69, v101, v69, vcc quad_perm:[2,3,0,1] row_mask:0xf bank_mask:0xf
	v_cndmask_b32_dpp v143, v142, v143, vcc quad_perm:[2,3,0,1] row_mask:0xf bank_mask:0xf
	v_cndmask_b32_dpp v5, v37, v5, vcc quad_perm:[2,3,0,1] row_mask:0xf bank_mask:0xf
	v_cvt_pk_bf16_f32 v117, v117, v85
	v_cvt_pk_bf16_f32 v101, v141, v69
	v_cvt_pk_bf16_f32 v53, v53, v21
	v_cvt_pk_bf16_f32 v37, v143, v5
	ds_bpermute_b32 v168, v176, v117
	ds_bpermute_b32 v169, v176, v101
	ds_bpermute_b32 v170, v176, v53
	ds_bpermute_b32 v171, v176, v37
	s_waitcnt lgkmcnt(4)
	global_store_dwordx2 v[186:187], v[172:173], off
	global_store_dwordx2 v[186:187], v[174:175], off offset:256
	s_waitcnt lgkmcnt(0)
	global_store_dwordx2 v[188:189], v[168:169], off
	global_store_dwordx2 v[188:189], v[170:171], off offset:256
	s_branch .LBB0_1237
